# S5 a1 stage: LDS fragment reads batched six steps deep into free registers (fixed accumulators) instead of read-wait-MFMA per step
# speedup vs baseline: 1.0072x; 1.0072x over previous
.LBB0_735:
	s_or_b64 exec, exec, s[6:7]
	v_and_b32_e32 v225, 15, v2
	v_mul_u32_u24_e32 v224, 0x810, v225
	v_and_b32_e32 v228, 48, v2
	v_add3_u32 v3, 0, v224, v228
	s_waitcnt lgkmcnt(0)
	s_barrier
	ds_read_b128 v[150:153], v3
	ds_read_b128 v[154:157], v3 offset:33024
	ds_read_b128 v[158:161], v3 offset:64
	ds_read_b128 v[162:165], v3 offset:33088
	ds_read_b128 v[166:169], v3 offset:128
	ds_read_b128 v[170:173], v3 offset:33152
	ds_read_b128 v[174:177], v3 offset:192
	ds_read_b128 v[178:181], v3 offset:33216
	ds_read_b128 v[182:185], v3 offset:256
	ds_read_b128 v[186:189], v3 offset:33280
	ds_read_b128 v[190:193], v3 offset:320
	ds_read_b128 v[194:197], v3 offset:33344
	s_waitcnt lgkmcnt(10)
	v_mfma_f32_16x16x32_bf16 v[138:141], v[132:135], v[150:153], 0
	v_mfma_f32_16x16x32_bf16 v[142:145], v[132:135], v[154:157], 0
	s_nop 7
	ds_read_b128 v[150:153], v3 offset:384
	ds_read_b128 v[154:157], v3 offset:33408
	s_waitcnt lgkmcnt(10)
	v_mfma_f32_16x16x32_bf16 v[138:141], v[128:131], v[158:161], v[138:141]
	v_mfma_f32_16x16x32_bf16 v[142:145], v[128:131], v[162:165], v[142:145]
	s_nop 7
	ds_read_b128 v[158:161], v3 offset:448
	ds_read_b128 v[162:165], v3 offset:33472
	s_waitcnt lgkmcnt(10)
	v_mfma_f32_16x16x32_bf16 v[138:141], v[124:127], v[166:169], v[138:141]
	v_mfma_f32_16x16x32_bf16 v[142:145], v[124:127], v[170:173], v[142:145]
	s_nop 7
	ds_read_b128 v[166:169], v3 offset:512
	ds_read_b128 v[170:173], v3 offset:33536
	s_waitcnt lgkmcnt(10)
	v_mfma_f32_16x16x32_bf16 v[138:141], v[116:119], v[174:177], v[138:141]
	v_mfma_f32_16x16x32_bf16 v[142:145], v[116:119], v[178:181], v[142:145]
	s_nop 7
	ds_read_b128 v[174:177], v3 offset:576
	ds_read_b128 v[178:181], v3 offset:33600
	s_waitcnt lgkmcnt(10)
	v_mfma_f32_16x16x32_bf16 v[138:141], v[120:123], v[182:185], v[138:141]
	v_mfma_f32_16x16x32_bf16 v[142:145], v[120:123], v[186:189], v[142:145]
	s_nop 7
	ds_read_b128 v[182:185], v3 offset:640
	ds_read_b128 v[186:189], v3 offset:33664
	s_waitcnt lgkmcnt(10)
	v_mfma_f32_16x16x32_bf16 v[138:141], v[112:115], v[190:193], v[138:141]
	v_mfma_f32_16x16x32_bf16 v[142:145], v[112:115], v[194:197], v[142:145]
	s_nop 7
	ds_read_b128 v[190:193], v3 offset:704
	ds_read_b128 v[194:197], v3 offset:33728
	s_waitcnt lgkmcnt(10)
	v_mfma_f32_16x16x32_bf16 v[138:141], v[108:111], v[150:153], v[138:141]
	v_mfma_f32_16x16x32_bf16 v[142:145], v[108:111], v[154:157], v[142:145]
	s_nop 7
	ds_read_b128 v[150:153], v3 offset:768
	ds_read_b128 v[154:157], v3 offset:33792
	s_waitcnt lgkmcnt(10)
	v_mfma_f32_16x16x32_bf16 v[138:141], v[104:107], v[158:161], v[138:141]
	v_mfma_f32_16x16x32_bf16 v[142:145], v[104:107], v[162:165], v[142:145]
	s_nop 7
	ds_read_b128 v[158:161], v3 offset:832
	ds_read_b128 v[162:165], v3 offset:33856
	s_waitcnt lgkmcnt(10)
	v_mfma_f32_16x16x32_bf16 v[138:141], v[100:103], v[166:169], v[138:141]
	v_mfma_f32_16x16x32_bf16 v[142:145], v[100:103], v[170:173], v[142:145]
	s_nop 7
	ds_read_b128 v[166:169], v3 offset:896
	ds_read_b128 v[170:173], v3 offset:33920
	s_waitcnt lgkmcnt(10)
	v_mfma_f32_16x16x32_bf16 v[138:141], v[96:99], v[174:177], v[138:141]
	v_mfma_f32_16x16x32_bf16 v[142:145], v[96:99], v[178:181], v[142:145]
	s_nop 7
	ds_read_b128 v[174:177], v3 offset:960
	ds_read_b128 v[178:181], v3 offset:33984
	s_waitcnt lgkmcnt(10)
	v_mfma_f32_16x16x32_bf16 v[138:141], v[92:95], v[182:185], v[138:141]
	v_mfma_f32_16x16x32_bf16 v[142:145], v[92:95], v[186:189], v[142:145]
	s_nop 7
	ds_read_b128 v[182:185], v3 offset:1024
	ds_read_b128 v[186:189], v3 offset:34048
	s_waitcnt lgkmcnt(10)
	v_mfma_f32_16x16x32_bf16 v[138:141], v[88:91], v[190:193], v[138:141]
	v_mfma_f32_16x16x32_bf16 v[142:145], v[88:91], v[194:197], v[142:145]
	s_nop 7
	ds_read_b128 v[190:193], v3 offset:1088
	ds_read_b128 v[194:197], v3 offset:34112
	s_waitcnt lgkmcnt(10)
	v_mfma_f32_16x16x32_bf16 v[138:141], v[84:87], v[150:153], v[138:141]
	v_mfma_f32_16x16x32_bf16 v[142:145], v[84:87], v[154:157], v[142:145]
	s_nop 7
	ds_read_b128 v[150:153], v3 offset:1152
	ds_read_b128 v[154:157], v3 offset:34176
	s_waitcnt lgkmcnt(10)
	v_mfma_f32_16x16x32_bf16 v[138:141], v[80:83], v[158:161], v[138:141]
	v_mfma_f32_16x16x32_bf16 v[142:145], v[80:83], v[162:165], v[142:145]
	s_nop 7
	ds_read_b128 v[158:161], v3 offset:1216
	ds_read_b128 v[162:165], v3 offset:34240
	s_waitcnt lgkmcnt(10)
	v_mfma_f32_16x16x32_bf16 v[138:141], v[76:79], v[166:169], v[138:141]
	v_mfma_f32_16x16x32_bf16 v[142:145], v[76:79], v[170:173], v[142:145]
	s_nop 7
	ds_read_b128 v[166:169], v3 offset:1280
	ds_read_b128 v[170:173], v3 offset:34304
	s_waitcnt lgkmcnt(10)
	v_mfma_f32_16x16x32_bf16 v[138:141], v[72:75], v[174:177], v[138:141]
	v_mfma_f32_16x16x32_bf16 v[142:145], v[72:75], v[178:181], v[142:145]
	s_nop 7
	ds_read_b128 v[174:177], v3 offset:1344
	ds_read_b128 v[178:181], v3 offset:34368
	s_waitcnt lgkmcnt(10)
	v_mfma_f32_16x16x32_bf16 v[138:141], v[68:71], v[182:185], v[138:141]
	v_mfma_f32_16x16x32_bf16 v[142:145], v[68:71], v[186:189], v[142:145]
	s_nop 7
	ds_read_b128 v[182:185], v3 offset:1408
	ds_read_b128 v[186:189], v3 offset:34432
	s_waitcnt lgkmcnt(10)
	v_mfma_f32_16x16x32_bf16 v[138:141], v[64:67], v[190:193], v[138:141]
	v_mfma_f32_16x16x32_bf16 v[142:145], v[64:67], v[194:197], v[142:145]
	s_nop 7
	ds_read_b128 v[190:193], v3 offset:1472
	ds_read_b128 v[194:197], v3 offset:34496
	s_waitcnt lgkmcnt(10)
	v_mfma_f32_16x16x32_bf16 v[138:141], v[60:63], v[150:153], v[138:141]
	v_mfma_f32_16x16x32_bf16 v[142:145], v[60:63], v[154:157], v[142:145]
	s_nop 7
	ds_read_b128 v[150:153], v3 offset:1536
	ds_read_b128 v[154:157], v3 offset:34560
	s_waitcnt lgkmcnt(10)
	v_mfma_f32_16x16x32_bf16 v[138:141], v[52:55], v[158:161], v[138:141]
	v_mfma_f32_16x16x32_bf16 v[142:145], v[52:55], v[162:165], v[142:145]
	s_nop 7
	ds_read_b128 v[158:161], v3 offset:1600
	ds_read_b128 v[162:165], v3 offset:34624
	s_waitcnt lgkmcnt(10)
	v_mfma_f32_16x16x32_bf16 v[138:141], v[56:59], v[166:169], v[138:141]
	v_mfma_f32_16x16x32_bf16 v[142:145], v[56:59], v[170:173], v[142:145]
	s_nop 7
	ds_read_b128 v[166:169], v3 offset:1664
	ds_read_b128 v[170:173], v3 offset:34688
	s_waitcnt lgkmcnt(10)
	v_mfma_f32_16x16x32_bf16 v[138:141], v[40:43], v[174:177], v[138:141]
	v_mfma_f32_16x16x32_bf16 v[142:145], v[40:43], v[178:181], v[142:145]
	s_nop 7
	ds_read_b128 v[174:177], v3 offset:1728
	ds_read_b128 v[178:181], v3 offset:34752
	s_waitcnt lgkmcnt(10)
	v_mfma_f32_16x16x32_bf16 v[138:141], v[36:39], v[182:185], v[138:141]
	v_mfma_f32_16x16x32_bf16 v[142:145], v[36:39], v[186:189], v[142:145]
	s_nop 7
	ds_read_b128 v[182:185], v3 offset:1792
	ds_read_b128 v[186:189], v3 offset:34816
	s_waitcnt lgkmcnt(10)
	v_mfma_f32_16x16x32_bf16 v[138:141], v[32:35], v[190:193], v[138:141]
	v_mfma_f32_16x16x32_bf16 v[142:145], v[32:35], v[194:197], v[142:145]
	s_nop 7
	ds_read_b128 v[190:193], v3 offset:1856
	ds_read_b128 v[194:197], v3 offset:34880
	s_waitcnt lgkmcnt(10)
	v_mfma_f32_16x16x32_bf16 v[138:141], v[28:31], v[150:153], v[138:141]
	v_mfma_f32_16x16x32_bf16 v[142:145], v[28:31], v[154:157], v[142:145]
	s_nop 7
	ds_read_b128 v[150:153], v3 offset:1920
	ds_read_b128 v[154:157], v3 offset:34944
	s_waitcnt lgkmcnt(10)
	v_mfma_f32_16x16x32_bf16 v[138:141], v[24:27], v[158:161], v[138:141]
	v_mfma_f32_16x16x32_bf16 v[142:145], v[24:27], v[162:165], v[142:145]
	s_nop 7
	ds_read_b128 v[158:161], v3 offset:1984
	ds_read_b128 v[162:165], v3 offset:35008
	s_waitcnt lgkmcnt(10)
	v_mfma_f32_16x16x32_bf16 v[138:141], v[20:23], v[166:169], v[138:141]
	v_mfma_f32_16x16x32_bf16 v[142:145], v[20:23], v[170:173], v[142:145]
	s_waitcnt lgkmcnt(8)
	v_mfma_f32_16x16x32_bf16 v[138:141], v[16:19], v[174:177], v[138:141]
	v_mfma_f32_16x16x32_bf16 v[142:145], v[16:19], v[178:181], v[142:145]
	s_waitcnt lgkmcnt(6)
	v_mfma_f32_16x16x32_bf16 v[138:141], v[12:15], v[182:185], v[138:141]
	v_mfma_f32_16x16x32_bf16 v[142:145], v[12:15], v[186:189], v[142:145]
	s_waitcnt lgkmcnt(4)
	v_mfma_f32_16x16x32_bf16 v[138:141], v[8:11], v[190:193], v[138:141]
	v_mfma_f32_16x16x32_bf16 v[142:145], v[8:11], v[194:197], v[142:145]
	s_waitcnt lgkmcnt(2)
	v_mfma_f32_16x16x32_bf16 v[138:141], v[48:51], v[150:153], v[138:141]
	v_mfma_f32_16x16x32_bf16 v[142:145], v[48:51], v[154:157], v[142:145]
	s_waitcnt lgkmcnt(0)
	v_mfma_f32_16x16x32_bf16 v[138:141], v[44:47], v[158:161], v[138:141]
	v_mfma_f32_16x16x32_bf16 v[142:145], v[44:47], v[162:165], v[142:145]
	s_nop 15
	v_mov_b32_e32 v12, v138
	v_mov_b32_e32 v13, v139
	v_mov_b32_e32 v14, v140
	v_mov_b32_e32 v15, v141
	v_mov_b32_e32 v8, v142
	v_mov_b32_e32 v9, v143
	v_mov_b32_e32 v10, v144
	v_mov_b32_e32 v11, v145
	v_bfe_u32 v227, v2, 4, 2
	s_lshl_b32 s12, s27, 4
	v_lshlrev_b32_e32 v226, 2, v227
	s_add_u32 s6, s17, s33
	s_movk_i32 s13, 0x84
	s_addc_u32 s7, s18, 0
	v_cmp_gt_i32_e32 vcc, 64, v2
	v_lshl_add_u64 v[128:129], s[6:7], 0, v[0:1]
	v_lshl_or_b32 v3, s39, 4, v226
	v_mul_lo_u32 v3, v3, s13
	v_lshlrev_b32_e32 v16, 2, v225
	v_readlane_b32 s13, v254, 29
	v_add3_u32 v3, s13, v3, v16
	s_nop 1
	ds_write2_b32 v3, v12, v8 offset1:16
	ds_write2_b32 v3, v13, v9 offset0:33 offset1:49
	ds_write2_b32 v3, v14, v10 offset0:66 offset1:82
	ds_write2_b32 v3, v15, v11 offset0:99 offset1:115
	v_lshl_add_u64 v[8:9], v[128:129], 0, s[2:3]
	s_or_b32 s2, s0, 1
	s_ashr_i32 s3, s2, 31
	s_lshl_b64 s[2:3], s[2:3], 10
	v_lshl_add_u64 v[12:13], v[128:129], 0, s[2:3]
	s_or_b32 s2, s0, 2
	s_ashr_i32 s3, s2, 31
	s_lshl_b64 s[2:3], s[2:3], 10
	v_lshl_add_u64 v[16:17], v[128:129], 0, s[2:3]
	s_or_b32 s2, s0, 3
	s_ashr_i32 s3, s2, 31
	s_lshl_b64 s[2:3], s[2:3], 10
	v_lshl_add_u64 v[20:21], v[128:129], 0, s[2:3]
	s_or_b32 s2, s0, 4
	s_ashr_i32 s3, s2, 31
	s_lshl_b64 s[2:3], s[2:3], 10
	global_load_dwordx4 v[16:19], v[16:17], off
	s_nop 0
	global_load_dwordx4 v[24:27], v[20:21], off
	v_lshl_add_u64 v[20:21], v[128:129], 0, s[2:3]
	s_or_b32 s2, s0, 5
	s_ashr_i32 s3, s2, 31
	s_lshl_b64 s[2:3], s[2:3], 10
	global_load_dwordx4 v[28:31], v[20:21], off
	v_lshl_add_u64 v[20:21], v[128:129], 0, s[2:3]
	s_or_b32 s2, s0, 6
	s_ashr_i32 s3, s2, 31
	s_lshl_b64 s[2:3], s[2:3], 10
	global_load_dwordx4 v[40:43], v[20:21], off
	v_lshl_add_u64 v[20:21], v[128:129], 0, s[2:3]
	s_or_b32 s2, s0, 7
	s_ashr_i32 s3, s2, 31
	s_lshl_b64 s[2:3], s[2:3], 10
	global_load_dwordx4 v[48:51], v[20:21], off
	v_lshl_add_u64 v[20:21], v[128:129], 0, s[2:3]
	s_or_b32 s2, s0, 8
	s_ashr_i32 s3, s2, 31
	s_lshl_b64 s[2:3], s[2:3], 10
	global_load_dwordx4 v[64:67], v[20:21], off
	v_lshl_add_u64 v[20:21], v[128:129], 0, s[2:3]
	s_or_b32 s2, s0, 9
	s_ashr_i32 s3, s2, 31
	s_lshl_b64 s[2:3], s[2:3], 10
	v_lshl_add_u64 v[32:33], v[128:129], 0, s[2:3]
	s_or_b32 s2, s0, 10
	s_ashr_i32 s3, s2, 31
	s_lshl_b64 s[2:3], s[2:3], 10
	v_lshl_add_u64 v[36:37], v[128:129], 0, s[2:3]
	s_or_b32 s2, s0, 11
	s_ashr_i32 s3, s2, 31
	s_lshl_b64 s[2:3], s[2:3], 10
	v_lshl_add_u64 v[44:45], v[128:129], 0, s[2:3]
	s_or_b32 s2, s0, 12
	s_ashr_i32 s3, s2, 31
	s_lshl_b64 s[2:3], s[2:3], 10
	global_load_dwordx4 v[36:39], v[36:37], off
	s_nop 0
	global_load_dwordx4 v[52:55], v[44:45], off
	v_lshl_add_u64 v[44:45], v[128:129], 0, s[2:3]
	s_or_b32 s2, s0, 13
	s_ashr_i32 s3, s2, 31
	s_lshl_b64 s[2:3], s[2:3], 10
	global_load_dwordx4 v[56:59], v[44:45], off
	v_lshl_add_u64 v[44:45], v[128:129], 0, s[2:3]
	s_or_b32 s2, s0, 14
	s_ashr_i32 s3, s2, 31
	s_lshl_b64 s[2:3], s[2:3], 10
	global_load_dwordx4 v[76:79], v[44:45], off
	v_lshl_add_u64 v[44:45], v[128:129], 0, s[2:3]
	s_or_b32 s2, s0, 15
	s_ashr_i32 s3, s2, 31
	s_lshl_b64 s[2:3], s[2:3], 10
	global_load_dwordx4 v[84:87], v[44:45], off
	v_lshl_add_u64 v[44:45], v[128:129], 0, s[2:3]
	s_or_b32 s2, s0, 16
	s_ashr_i32 s3, s2, 31
	s_lshl_b64 s[2:3], s[2:3], 10
	global_load_dwordx4 v[108:111], v[44:45], off
	v_lshl_add_u64 v[44:45], v[128:129], 0, s[2:3]
	s_or_b32 s2, s0, 17
	s_ashr_i32 s3, s2, 31
	s_lshl_b64 s[2:3], s[2:3], 10
	v_lshl_add_u64 v[60:61], v[128:129], 0, s[2:3]
	s_or_b32 s2, s0, 18
	s_ashr_i32 s3, s2, 31
	s_lshl_b64 s[2:3], s[2:3], 10
	v_lshl_add_u64 v[68:69], v[128:129], 0, s[2:3]
	s_or_b32 s2, s0, 19
	s_ashr_i32 s3, s2, 31
	s_lshl_b64 s[2:3], s[2:3], 10
	v_lshl_add_u64 v[72:73], v[128:129], 0, s[2:3]
	s_or_b32 s2, s0, 20
	s_ashr_i32 s3, s2, 31
	s_lshl_b64 s[2:3], s[2:3], 10
	global_load_dwordx4 v[68:71], v[68:69], off
	s_nop 0
	global_load_dwordx4 v[92:95], v[72:73], off
	v_lshl_add_u64 v[72:73], v[128:129], 0, s[2:3]
	s_or_b32 s2, s0, 21
	s_ashr_i32 s3, s2, 31
	s_lshl_b64 s[2:3], s[2:3], 10
	global_load_dwordx4 v[96:99], v[72:73], off
	v_lshl_add_u64 v[72:73], v[128:129], 0, s[2:3]
	s_or_b32 s2, s0, 22
	s_ashr_i32 s3, s2, 31
	s_lshl_b64 s[2:3], s[2:3], 10
	global_load_dwordx4 v[112:115], v[72:73], off
	v_lshl_add_u64 v[72:73], v[128:129], 0, s[2:3]
	s_or_b32 s2, s0, 23
	s_ashr_i32 s3, s2, 31
	s_lshl_b64 s[2:3], s[2:3], 10
	global_load_dwordx4 v[124:127], v[72:73], off
	v_lshl_add_u64 v[72:73], v[128:129], 0, s[2:3]
	s_or_b32 s2, s0, 24
	s_ashr_i32 s3, s2, 31
	s_lshl_b64 s[2:3], s[2:3], 10
	global_load_dwordx4 v[132:135], v[72:73], off
	v_lshl_add_u64 v[72:73], v[128:129], 0, s[2:3]
	s_or_b32 s2, s0, 25
	s_ashr_i32 s3, s2, 31
	s_lshl_b64 s[2:3], s[2:3], 10
	v_lshl_add_u64 v[80:81], v[128:129], 0, s[2:3]
	s_or_b32 s2, s0, 26
	s_ashr_i32 s3, s2, 31
	s_lshl_b64 s[2:3], s[2:3], 10
	v_lshl_add_u64 v[88:89], v[128:129], 0, s[2:3]
	s_or_b32 s2, s0, 27
	s_ashr_i32 s3, s2, 31
	s_lshl_b64 s[2:3], s[2:3], 10
	v_lshl_add_u64 v[100:101], v[128:129], 0, s[2:3]
	s_or_b32 s2, s0, 28
	s_ashr_i32 s3, s2, 31
	s_lshl_b64 s[2:3], s[2:3], 10
	v_lshl_add_u64 v[104:105], v[128:129], 0, s[2:3]
	s_or_b32 s2, s0, 29
	s_ashr_i32 s3, s2, 31
	s_lshl_b64 s[2:3], s[2:3], 10
	v_lshl_add_u64 v[116:117], v[128:129], 0, s[2:3]
	s_or_b32 s2, s0, 30
	s_ashr_i32 s3, s2, 31
	s_lshl_b64 s[2:3], s[2:3], 10
	v_lshl_add_u64 v[120:121], v[128:129], 0, s[2:3]
	s_or_b32 s2, s0, 31
	s_ashr_i32 s3, s2, 31
	s_lshl_b64 s[2:3], s[2:3], 10
	v_lshl_add_u64 v[128:129], v[128:129], 0, s[2:3]
	global_load_dwordx4 v[8:11], v[8:9], off
	s_nop 0
	global_load_dwordx4 v[12:15], v[12:13], off
	s_nop 0
	global_load_dwordx4 v[20:23], v[20:21], off
	s_nop 0
	global_load_dwordx4 v[32:35], v[32:33], off
	s_nop 0
	global_load_dwordx4 v[44:47], v[44:45], off
	s_nop 0
	global_load_dwordx4 v[60:63], v[60:61], off
	s_nop 0
	global_load_dwordx4 v[72:75], v[72:73], off
	s_nop 0
	global_load_dwordx4 v[80:83], v[80:81], off
	s_nop 0
	global_load_dwordx4 v[88:91], v[88:89], off
	s_nop 0
	global_load_dwordx4 v[100:103], v[100:101], off
	s_nop 0
	global_load_dwordx4 v[104:107], v[104:105], off
	s_nop 0
	global_load_dwordx4 v[116:119], v[116:117], off
	s_nop 0
	global_load_dwordx4 v[120:123], v[120:121], off
	s_nop 0
	global_load_dwordx4 v[128:131], v[128:129], off
	s_waitcnt lgkmcnt(0)
	s_barrier
	s_and_saveexec_b64 s[2:3], vcc
	s_cbranch_execz .LBB0_737
	s_movk_i32 s6, 0x84
	v_mul_lo_u32 v3, v2, s6
	v_add_u32_e32 v3, 0, v3
	v_add_u32_e32 v3, 0x18400, v3
	v_add_u32_e32 v139, 0x2108, v3
	v_add_u32_e32 v142, 0x2120, v3
	v_add_u32_e32 v140, 0x2110, v3
	ds_read2_b32 v[168:169], v3 offset1:1
	ds_read2_b32 v[170:171], v3 offset0:2 offset1:3
	ds_read2_b32 v[172:173], v3 offset0:4 offset1:5
	ds_read2_b32 v[174:175], v3 offset0:6 offset1:7
	v_add_u32_e32 v141, 0x2118, v3
	ds_read2_b32 v[176:177], v139 offset1:1
	ds_read2_b32 v[178:179], v140 offset1:1
	ds_read2_b32 v[180:181], v141 offset1:1
	ds_read2_b32 v[182:183], v142 offset1:1
	v_add_u32_e32 v139, 0x2128, v3
	v_add_u32_e32 v142, 0x2140, v3
	v_add_u32_e32 v138, 0x2100, v3
	v_add_u32_e32 v140, 0x2130, v3
	ds_read2_b32 v[184:185], v3 offset0:8 offset1:9
	ds_read2_b32 v[186:187], v3 offset0:10 offset1:11
	ds_read2_b32 v[188:189], v3 offset0:12 offset1:13
	ds_read2_b32 v[190:191], v3 offset0:14 offset1:15
	v_add_u32_e32 v141, 0x2138, v3
	ds_read2_b32 v[192:193], v139 offset1:1
	ds_read2_b32 v[194:195], v140 offset1:1
	ds_read2_b32 v[196:197], v141 offset1:1
	ds_read2_b32 v[164:165], v142 offset1:1
	v_add_u32_e32 v139, 0x2148, v3
	v_add_u32_e32 v142, 0x2160, v3
	v_mul_f32_e32 v229, 0, v137
	v_add_u32_e32 v140, 0x2150, v3
	ds_read2_b32 v[166:167], v3 offset0:16 offset1:17
	ds_read2_b32 v[160:161], v3 offset0:18 offset1:19
	ds_read2_b32 v[156:157], v3 offset0:20 offset1:21
	ds_read2_b32 v[152:153], v3 offset0:22 offset1:23
	v_add_u32_e32 v141, 0x2158, v3
	ds_read2_b32 v[162:163], v139 offset1:1
	ds_read2_b32 v[158:159], v140 offset1:1
	ds_read2_b32 v[154:155], v141 offset1:1
	ds_read2_b32 v[148:149], v142 offset1:1
	ds_read2_b32 v[198:199], v138 offset1:1
	ds_read2_b32 v[150:151], v3 offset0:24 offset1:25
	ds_read2_b32 v[144:145], v3 offset0:26 offset1:27
	ds_read2_b32 v[142:143], v3 offset0:28 offset1:29
	v_fma_f32 v230, v136, 0, -v229
	v_add_u32_e32 v139, 0x2168, v3
	v_add_u32_e32 v138, 0x2170, v3
	v_add_u32_e32 v3, 0x78, v3
	s_waitcnt lgkmcnt(14)
	v_add_f32_e32 v168, v230, v168
	v_fmac_f32_e32 v229, 0, v136
	ds_read2_b32 v[146:147], v139 offset1:1
	ds_read2_b32 v[140:141], v138 offset1:1
	ds_read2st64_b32 v[138:139], v3 offset1:33
	v_lshl_add_u32 v3, v2, 1, 0
	s_waitcnt lgkmcnt(6)
	v_add_f32_e32 v198, v229, v198
	v_bfe_u32 v229, v168, 16, 1
	v_add_u32_e32 v3, 0x1c600, v3
	v_add3_u32 v229, v168, v229, s23
	ds_write_b16 v3, v1
	ds_write_b16 v3, v1 offset:128
	ds_write_b16_d16_hi v3, v229 offset:272
	v_bfe_u32 v229, v198, 16, 1
	v_add3_u32 v229, v198, v229, s23
	ds_write_b16_d16_hi v3, v229 offset:400
	v_mul_f32_e32 v229, v137, v198
	v_fma_f32 v229, v136, v168, -v229
	v_mul_f32_e32 v198, v136, v198
	v_add_f32_e32 v169, v169, v229
	v_fmac_f32_e32 v198, v137, v168
	v_add_f32_e32 v168, v199, v198
	v_bfe_u32 v198, v169, 16, 1
	v_add3_u32 v198, v169, v198, s23
	ds_write_b16_d16_hi v3, v198 offset:544
	v_bfe_u32 v198, v168, 16, 1
	v_add3_u32 v198, v168, v198, s23
	ds_write_b16_d16_hi v3, v198 offset:672
	v_mul_f32_e32 v198, v137, v168
	v_fma_f32 v198, v136, v169, -v198
	v_mul_f32_e32 v169, v137, v169
	v_add_f32_e32 v170, v170, v198
	v_fmac_f32_e32 v169, v136, v168
	v_add_f32_e32 v168, v176, v169
	v_bfe_u32 v169, v170, 16, 1
	v_add3_u32 v169, v170, v169, s23
	ds_write_b16_d16_hi v3, v169 offset:816
	v_bfe_u32 v169, v168, 16, 1
	v_add3_u32 v169, v168, v169, s23
	ds_write_b16_d16_hi v3, v169 offset:944
	v_mul_f32_e32 v169, v137, v168
	v_fma_f32 v169, v136, v170, -v169
	v_mul_f32_e32 v170, v137, v170
	v_add_f32_e32 v169, v171, v169
	v_fmac_f32_e32 v170, v136, v168
	v_add_f32_e32 v168, v177, v170
	v_bfe_u32 v170, v169, 16, 1
	v_add3_u32 v170, v169, v170, s23
	ds_write_b16_d16_hi v3, v170 offset:1088
	v_bfe_u32 v170, v168, 16, 1
	v_add3_u32 v170, v168, v170, s23
	ds_write_b16_d16_hi v3, v170 offset:1216
	v_mul_f32_e32 v170, v137, v168
	v_fma_f32 v170, v136, v169, -v170
	v_mul_f32_e32 v169, v137, v169
	v_add_f32_e32 v170, v172, v170
	v_fmac_f32_e32 v169, v136, v168
	v_add_f32_e32 v168, v178, v169
	v_bfe_u32 v169, v170, 16, 1
	v_add3_u32 v169, v170, v169, s23
	ds_write_b16_d16_hi v3, v169 offset:1360
	v_bfe_u32 v169, v168, 16, 1
	v_add3_u32 v169, v168, v169, s23
	ds_write_b16_d16_hi v3, v169 offset:1488
	v_mul_f32_e32 v169, v137, v168
	v_fma_f32 v169, v136, v170, -v169
	v_mul_f32_e32 v170, v137, v170
	v_add_f32_e32 v169, v173, v169
	v_fmac_f32_e32 v170, v136, v168
	v_add_f32_e32 v168, v179, v170
	v_bfe_u32 v170, v169, 16, 1
	v_add3_u32 v170, v169, v170, s23
	ds_write_b16_d16_hi v3, v170 offset:1632
	v_bfe_u32 v170, v168, 16, 1
	v_add3_u32 v170, v168, v170, s23
	ds_write_b16_d16_hi v3, v170 offset:1760
	v_mul_f32_e32 v170, v137, v168
	v_fma_f32 v170, v136, v169, -v170
	v_mul_f32_e32 v169, v137, v169
	v_add_f32_e32 v170, v174, v170
	v_fmac_f32_e32 v169, v136, v168
	v_add_f32_e32 v168, v180, v169
	v_bfe_u32 v169, v170, 16, 1
	v_add3_u32 v169, v170, v169, s23
	ds_write_b16_d16_hi v3, v169 offset:1904
	v_bfe_u32 v169, v168, 16, 1
	v_add3_u32 v169, v168, v169, s23
	ds_write_b16_d16_hi v3, v169 offset:2032
	v_mul_f32_e32 v169, v137, v168
	v_fma_f32 v169, v136, v170, -v169
	v_mul_f32_e32 v170, v137, v170
	v_add_f32_e32 v169, v175, v169
	v_fmac_f32_e32 v170, v136, v168
	v_add_f32_e32 v168, v181, v170
	v_bfe_u32 v170, v169, 16, 1
	v_add3_u32 v170, v169, v170, s23
	ds_write_b16_d16_hi v3, v170 offset:2176
	v_bfe_u32 v170, v168, 16, 1
	v_add3_u32 v170, v168, v170, s23
	ds_write_b16_d16_hi v3, v170 offset:2304
	v_mul_f32_e32 v170, v137, v168
	v_fma_f32 v170, v136, v169, -v170
	v_mul_f32_e32 v169, v137, v169
	v_add_f32_e32 v170, v184, v170
	v_fmac_f32_e32 v169, v136, v168
	v_add_f32_e32 v168, v182, v169
	v_bfe_u32 v169, v170, 16, 1
	v_add3_u32 v169, v170, v169, s23
	ds_write_b16_d16_hi v3, v169 offset:2448
	v_bfe_u32 v169, v168, 16, 1
	v_add3_u32 v169, v168, v169, s23
	ds_write_b16_d16_hi v3, v169 offset:2576
	v_mul_f32_e32 v169, v137, v168
	v_fma_f32 v169, v136, v170, -v169
	v_mul_f32_e32 v170, v137, v170
	v_add_f32_e32 v169, v185, v169
	v_fmac_f32_e32 v170, v136, v168
	v_add_f32_e32 v168, v183, v170
	v_bfe_u32 v170, v169, 16, 1
	v_add3_u32 v170, v169, v170, s23
	ds_write_b16_d16_hi v3, v170 offset:2720
	v_bfe_u32 v170, v168, 16, 1
	v_add3_u32 v170, v168, v170, s23
	ds_write_b16_d16_hi v3, v170 offset:2848
	v_mul_f32_e32 v170, v137, v168
	v_fma_f32 v170, v136, v169, -v170
	v_mul_f32_e32 v169, v137, v169
	v_add_f32_e32 v170, v186, v170
	v_fmac_f32_e32 v169, v136, v168
	v_add_f32_e32 v168, v192, v169
	v_bfe_u32 v169, v170, 16, 1
	v_add3_u32 v169, v170, v169, s23
	ds_write_b16_d16_hi v3, v169 offset:2992
	v_bfe_u32 v169, v168, 16, 1
	v_add3_u32 v169, v168, v169, s23
	ds_write_b16_d16_hi v3, v169 offset:3120
	v_mul_f32_e32 v169, v137, v168
	v_fma_f32 v169, v136, v170, -v169
	v_mul_f32_e32 v170, v137, v170
	v_add_f32_e32 v169, v187, v169
	v_fmac_f32_e32 v170, v136, v168
	v_add_f32_e32 v168, v193, v170
	v_bfe_u32 v170, v169, 16, 1
	v_add3_u32 v170, v169, v170, s23
	ds_write_b16_d16_hi v3, v170 offset:3264
	v_bfe_u32 v170, v168, 16, 1
	v_add3_u32 v170, v168, v170, s23
	ds_write_b16_d16_hi v3, v170 offset:3392
	v_mul_f32_e32 v170, v137, v168
	v_fma_f32 v170, v136, v169, -v170
	v_mul_f32_e32 v169, v137, v169
	v_add_f32_e32 v170, v188, v170
	v_fmac_f32_e32 v169, v136, v168
	v_add_f32_e32 v168, v194, v169
	v_bfe_u32 v169, v170, 16, 1
	v_add3_u32 v169, v170, v169, s23
	ds_write_b16_d16_hi v3, v169 offset:3536
	v_bfe_u32 v169, v168, 16, 1
	v_add3_u32 v169, v168, v169, s23
	ds_write_b16_d16_hi v3, v169 offset:3664
	v_mul_f32_e32 v169, v137, v168
	v_fma_f32 v169, v136, v170, -v169
	v_mul_f32_e32 v170, v137, v170
	v_add_f32_e32 v169, v189, v169
	v_fmac_f32_e32 v170, v136, v168
	v_add_f32_e32 v168, v195, v170
	v_bfe_u32 v170, v169, 16, 1
	v_add3_u32 v170, v169, v170, s23
	ds_write_b16_d16_hi v3, v170 offset:3808
	v_bfe_u32 v170, v168, 16, 1
	v_add3_u32 v170, v168, v170, s23
	ds_write_b16_d16_hi v3, v170 offset:3936
	v_mul_f32_e32 v170, v137, v168
	v_fma_f32 v170, v136, v169, -v170
	v_mul_f32_e32 v169, v137, v169
	v_add_f32_e32 v170, v190, v170
	v_fmac_f32_e32 v169, v136, v168
	v_add_f32_e32 v168, v196, v169
	v_bfe_u32 v169, v170, 16, 1
	v_add3_u32 v169, v170, v169, s23
	ds_write_b16_d16_hi v3, v169 offset:4080
	v_bfe_u32 v169, v168, 16, 1
	v_add3_u32 v169, v168, v169, s23
	ds_write_b16_d16_hi v3, v169 offset:4208
	v_mul_f32_e32 v169, v137, v168
	v_fma_f32 v169, v136, v170, -v169
	v_mul_f32_e32 v170, v137, v170
	v_add_f32_e32 v169, v191, v169
	v_fmac_f32_e32 v170, v136, v168
	v_add_f32_e32 v168, v197, v170
	v_bfe_u32 v170, v169, 16, 1
	v_add3_u32 v170, v169, v170, s23
	ds_write_b16_d16_hi v3, v170 offset:4352
	v_bfe_u32 v170, v168, 16, 1
	v_add3_u32 v170, v168, v170, s23
	ds_write_b16_d16_hi v3, v170 offset:4480
	v_mul_f32_e32 v170, v137, v168
	v_fma_f32 v170, v136, v169, -v170
	v_add_f32_e32 v166, v166, v170
	v_mul_f32_e32 v169, v137, v169
	v_fmac_f32_e32 v169, v136, v168
	v_bfe_u32 v168, v166, 16, 1
	v_add_f32_e32 v164, v164, v169
	v_add3_u32 v168, v166, v168, s23
	ds_write_b16_d16_hi v3, v168 offset:4624
	v_bfe_u32 v168, v164, 16, 1
	v_add3_u32 v168, v164, v168, s23
	ds_write_b16_d16_hi v3, v168 offset:4752
	v_mul_f32_e32 v168, v137, v164
	v_fma_f32 v168, v136, v166, -v168
	v_mul_f32_e32 v166, v137, v166
	v_add_f32_e32 v167, v167, v168
	v_fmac_f32_e32 v166, v136, v164
	v_add_f32_e32 v164, v165, v166
	v_bfe_u32 v165, v167, 16, 1
	v_add3_u32 v165, v167, v165, s23
	ds_write_b16_d16_hi v3, v165 offset:4896
	v_bfe_u32 v165, v164, 16, 1
	v_add3_u32 v165, v164, v165, s23
	ds_write_b16_d16_hi v3, v165 offset:5024
	v_mul_f32_e32 v165, v137, v164
	v_fma_f32 v165, v136, v167, -v165
	v_add_f32_e32 v160, v160, v165
	v_mul_f32_e32 v165, v137, v167
	v_fmac_f32_e32 v165, v136, v164
	v_bfe_u32 v164, v160, 16, 1
	v_add_f32_e32 v162, v162, v165
	v_add3_u32 v164, v160, v164, s23
	ds_write_b16_d16_hi v3, v164 offset:5168
	v_bfe_u32 v164, v162, 16, 1
	v_add3_u32 v164, v162, v164, s23
	ds_write_b16_d16_hi v3, v164 offset:5296
	v_mul_f32_e32 v164, v137, v162
	v_fma_f32 v164, v136, v160, -v164
	v_add_f32_e32 v161, v161, v164
	v_mul_f32_e32 v160, v137, v160
	v_fmac_f32_e32 v160, v136, v162
	v_bfe_u32 v162, v161, 16, 1
	v_add_f32_e32 v160, v163, v160
	v_add3_u32 v162, v161, v162, s23
	ds_write_b16_d16_hi v3, v162 offset:5440
	v_bfe_u32 v162, v160, 16, 1
	v_add3_u32 v162, v160, v162, s23
	ds_write_b16_d16_hi v3, v162 offset:5568
	v_mul_f32_e32 v162, v137, v160
	v_fma_f32 v162, v136, v161, -v162
	v_add_f32_e32 v156, v156, v162
	v_mul_f32_e32 v161, v137, v161
	v_fmac_f32_e32 v161, v136, v160
	v_bfe_u32 v160, v156, 16, 1
	v_add_f32_e32 v158, v158, v161
	v_add3_u32 v160, v156, v160, s23
	ds_write_b16_d16_hi v3, v160 offset:5712
	v_bfe_u32 v160, v158, 16, 1
	v_add3_u32 v160, v158, v160, s23
	ds_write_b16_d16_hi v3, v160 offset:5840
	v_mul_f32_e32 v160, v137, v158
	v_fma_f32 v160, v136, v156, -v160
	v_add_f32_e32 v157, v157, v160
	v_mul_f32_e32 v156, v137, v156
	v_fmac_f32_e32 v156, v136, v158
	v_bfe_u32 v158, v157, 16, 1
	v_add_f32_e32 v156, v159, v156
	v_add3_u32 v158, v157, v158, s23
	ds_write_b16_d16_hi v3, v158 offset:5984
	v_bfe_u32 v158, v156, 16, 1
	v_add3_u32 v158, v156, v158, s23
	ds_write_b16_d16_hi v3, v158 offset:6112
	v_mul_f32_e32 v158, v137, v156
	v_fma_f32 v158, v136, v157, -v158
	v_add_f32_e32 v152, v152, v158
	v_mul_f32_e32 v157, v137, v157
	v_fmac_f32_e32 v157, v136, v156
	v_bfe_u32 v156, v152, 16, 1
	v_add_f32_e32 v154, v154, v157
	v_add3_u32 v156, v152, v156, s23
	ds_write_b16_d16_hi v3, v156 offset:6256
	v_bfe_u32 v156, v154, 16, 1
	v_add3_u32 v156, v154, v156, s23
	ds_write_b16_d16_hi v3, v156 offset:6384
	v_mul_f32_e32 v156, v137, v154
	v_fma_f32 v156, v136, v152, -v156
	v_add_f32_e32 v153, v153, v156
	v_mul_f32_e32 v152, v137, v152
	v_fmac_f32_e32 v152, v136, v154
	v_bfe_u32 v154, v153, 16, 1
	v_add_f32_e32 v152, v155, v152
	v_add3_u32 v154, v153, v154, s23
	ds_write_b16_d16_hi v3, v154 offset:6528
	v_bfe_u32 v154, v152, 16, 1
	v_add3_u32 v154, v152, v154, s23
	ds_write_b16_d16_hi v3, v154 offset:6656
	v_mul_f32_e32 v154, v137, v152
	v_fma_f32 v154, v136, v153, -v154
	s_waitcnt lgkmcnt(14)
	v_add_f32_e32 v150, v150, v154
	v_mul_f32_e32 v153, v137, v153
	v_fmac_f32_e32 v153, v136, v152
	v_bfe_u32 v152, v150, 16, 1
	v_add_f32_e32 v148, v148, v153
	v_add3_u32 v152, v150, v152, s23
	ds_write_b16_d16_hi v3, v152 offset:6800
	v_bfe_u32 v152, v148, 16, 1
	v_add3_u32 v152, v148, v152, s23
	ds_write_b16_d16_hi v3, v152 offset:6928
	v_mul_f32_e32 v152, v137, v148
	v_fma_f32 v152, v136, v150, -v152
	v_mul_f32_e32 v150, v137, v150
	v_add_f32_e32 v151, v151, v152
	v_fmac_f32_e32 v150, v136, v148
	v_add_f32_e32 v148, v149, v150
	v_bfe_u32 v149, v151, 16, 1
	v_add3_u32 v149, v151, v149, s23
	ds_write_b16_d16_hi v3, v149 offset:7072
	v_bfe_u32 v149, v148, 16, 1
	v_add3_u32 v149, v148, v149, s23
	ds_write_b16_d16_hi v3, v149 offset:7200
	v_mul_f32_e32 v149, v137, v148
	v_fma_f32 v149, v136, v151, -v149
	v_add_f32_e32 v144, v144, v149
	v_mul_f32_e32 v149, v137, v151
	v_fmac_f32_e32 v149, v136, v148
	v_bfe_u32 v148, v144, 16, 1
	v_add_f32_e32 v146, v146, v149
	v_add3_u32 v148, v144, v148, s23
	ds_write_b16_d16_hi v3, v148 offset:7344
	v_bfe_u32 v148, v146, 16, 1
	v_add3_u32 v148, v146, v148, s23
	ds_write_b16_d16_hi v3, v148 offset:7472
	v_mul_f32_e32 v148, v137, v146
	v_fma_f32 v148, v136, v144, -v148
	v_add_f32_e32 v145, v145, v148
	v_mul_f32_e32 v144, v137, v144
	v_fmac_f32_e32 v144, v136, v146
	v_bfe_u32 v146, v145, 16, 1
	v_add_f32_e32 v144, v147, v144
	v_add3_u32 v146, v145, v146, s23
	ds_write_b16_d16_hi v3, v146 offset:7616
	v_bfe_u32 v146, v144, 16, 1
	v_add3_u32 v146, v144, v146, s23
	ds_write_b16_d16_hi v3, v146 offset:7744
	v_mul_f32_e32 v146, v137, v144
	v_fma_f32 v146, v136, v145, -v146
	v_add_f32_e32 v142, v142, v146
	v_mul_f32_e32 v145, v137, v145
	v_fmac_f32_e32 v145, v136, v144
	v_bfe_u32 v144, v142, 16, 1
	v_add_f32_e32 v140, v140, v145
	v_add3_u32 v144, v142, v144, s23
	ds_write_b16_d16_hi v3, v144 offset:7888
	v_bfe_u32 v144, v140, 16, 1
	v_add3_u32 v144, v140, v144, s23
	ds_write_b16_d16_hi v3, v144 offset:8016
	v_mul_f32_e32 v144, v137, v140
	v_fma_f32 v144, v136, v142, -v144
	v_mul_f32_e32 v142, v137, v142
	v_add_f32_e32 v143, v143, v144
	v_fmac_f32_e32 v142, v136, v140
	v_add_f32_e32 v140, v141, v142
	v_bfe_u32 v141, v143, 16, 1
	v_add3_u32 v141, v143, v141, s23
	ds_write_b16_d16_hi v3, v141 offset:8160
	v_bfe_u32 v141, v140, 16, 1
	v_add3_u32 v141, v140, v141, s23
	ds_write_b16_d16_hi v3, v141 offset:8288
	v_mul_f32_e32 v141, v137, v140
	v_fma_f32 v141, v136, v143, -v141
	v_mul_f32_e32 v137, v137, v143
	v_add_f32_e32 v138, v138, v141
	v_fmac_f32_e32 v137, v136, v140
	v_add_f32_e32 v136, v139, v137
	v_bfe_u32 v137, v138, 16, 1
	v_add3_u32 v137, v138, v137, s23
	ds_write_b16_d16_hi v3, v137 offset:8432
	v_bfe_u32 v137, v136, 16, 1
	v_add3_u32 v136, v136, v137, s23
	ds_write_b16_d16_hi v3, v136 offset:8560
